# combination + cross-tile prefetch on odin + hand-pipelined final RMSNorm
# speedup vs baseline: 1.0029x; 1.0029x over previous
.Lg4_done:
	s_nop 7
	s_nop 7
	s_branch .LBB0_1518
.LBB0_1518:
	s_lshr_b32 s12, s10, 10
	s_cmp_gt_u32 s12, 2
	s_cbranch_scc1 .Lodin4_old
	v_lshl_or_b32 v116, v183, 3, v191
	v_lshrrev_b32_e32 v117, 6, v116
	v_and_b32_e32 v118, 63, v116
	v_lshlrev_b32_e32 v113, 11, v117
	v_add_u32_e32 v113, 0x10000, v113
	v_readfirstlane_b32 s6, v117
	v_and_b32_e32 v116, 31, v118
	v_lshl_add_u32 v112, v116, 1, v113
	v_lshrrev_b32_e32 v117, 5, v118
	v_lshl_add_u32 v112, v117, 8, v112
	v_lshl_add_u32 v113, v118, 4, v113
	v_lshlrev_b32_e32 v115, 2, v116
	v_lshl_add_u32 v115, v117, 14, v115
	v_lshrrev_b32_e32 v117, 2, v118
	v_and_b32_e32 v114, 3, v118
	v_lshlrev_b32_e32 v114, 4, v114
	v_lshl_add_u32 v114, v117, 11, v114
	s_lshr_b32 s7, s6, 1
	s_lshl_b32 s7, s7, 6
	s_add_u32 s7, s7, s11
	s_and_b32 s6, s6, 1
	s_lshl_b32 s6, s6, 6
	s_and_b32 s8, s10, 0x3ff
	s_add_u32 s6, s6, s8
	s_cmp_eq_u32 s12, 2
	s_cbranch_scc1 .Lodin4_vseg
	s_cmp_ge_u32 s11, 0x2000
	s_cbranch_scc1 .Lodin4_rope
